# GEMM tile order: gsz is always 8 for nM=128, so the general integer division at every tile head / row-scale search iteration becomes shift+mask (20 instances); attention loop placement kept
# baseline (speedup 1.0000x reference)
;     __device__ bool next(int i, Unit& u) const {
;     ...
;         int wgid = (int)L; { const int q = nwg / NXCD, r = nwg % NXCD, xcd = wgid % NXCD, off = wgid / NXCD; wgid = (xcd < r ? xcd * (q + 1) : r * (q + 1) + (xcd - r) * q) + off; }
;         const int nig = WGM * nN, gid = wgid / nig, fm = gid * WGM, gsz = (nM - fm) < WGM ? (nM - fm) : WGM;
;         u.pm = fm + ((wgid % nig) % gsz); u.pn = (wgid % nig) / gsz; return true;
.LBB0_159:
	s_ashr_i32 s36, s40, 3
	s_add_i32 s36, s42, s36
	s_ashr_i32 s37, s36, 31
	s_lshr_b32 s37, s37, 27
	s_add_i32 s37, s36, s37
	s_ashr_i32 s40, s37, 5
	s_lshl_b32 s41, s40, 3
	s_andn2_b32 s37, s37, 31
	s_sub_i32 s36, s36, s37
	s_lshr_b32 s96, s36, 3
	s_and_b32 s36, s36, 7
	s_add_i32 s59, s36, s41
	s_andn2_b64 vcc, exec, s[0:1]
	s_mov_b64 s[0:1], -1
	s_cbranch_vccnz .LBB0_147

;     __device__ bool next(int i, Unit& u) const {
;     ...
;         int wgid = (int)L; { const int q = nwg / NXCD, r = nwg % NXCD, xcd = wgid % NXCD, off = wgid / NXCD; wgid = (xcd < r ? xcd * (q + 1) : r * (q + 1) + (xcd - r) * q) + off; }
;         const int nig = WGM * nN, gid = wgid / nig, fm = gid * WGM, gsz = (nM - fm) < WGM ? (nM - fm) : WGM;
;         u.pm = fm + ((wgid % nig) % gsz); u.pn = (wgid % nig) / gsz; return true;
; __device__ __forceinline__ void build_rstab(RsTab& T, LAS unsigned char* lds, const float* ss, const StaticOrder& S) {
;     ...
;     for (int i = 0;; ++i) { Unit u; if (!S.next(i, u)) break; const int pm = u.pm;
;         if (pm == p0 || pm == p1 || pm == p2 || pm == p3) continue;
;         if (p0 < 0) p0 = pm; else if (p1 < 0) p1 = pm; else if (p2 < 0) p2 = pm; else if (p3 < 0) p3 = pm; }
.LBB0_224:
	v_cmp_gt_i64_e32 vcc, s[4:5], v[2:3]
	v_cmp_lt_i64_e64 s[0:1], s[4:5], v[0:1]
	s_cbranch_vccnz .LBB0_226
	s_ashr_i32 s6, s4, 31
	s_lshr_b32 s6, s6, 29
	s_add_i32 s6, s4, s6
	s_ashr_i32 s7, s6, 3
	s_and_b32 s6, s6, -8
	s_sub_i32 s6, s4, s6
	s_cmp_lt_i32 s6, 0
	s_cselect_b32 s11, s10, 0x160
	s_mul_i32 s6, s11, s6
	s_add_i32 s6, s6, s7
	s_mul_hi_i32 s7, s6, 0x2e8ba2e9
	s_lshr_b32 s11, s7, 31
	s_ashr_i32 s7, s7, 5
	s_add_i32 s7, s7, s11
	s_lshl_b32 s11, s7, 3
	s_mulk_i32 s7, 0xb0
	s_sub_i32 s6, s6, s7
	s_and_b32 s6, s6, 7
	s_add_i32 s11, s6, s11

;     __device__ bool next(int i, Unit& u) const {
;         const long L = (long)i * G + c; if (L >= nwg) return false;
;         int wgid = (int)L; { const int q = nwg / NXCD, r = nwg % NXCD, xcd = wgid % NXCD, off = wgid / NXCD; wgid = (xcd < r ? xcd * (q + 1) : r * (q + 1) + (xcd - r) * q) + off; }
;         const int nig = WGM * nN, gid = wgid / nig, fm = gid * WGM, gsz = (nM - fm) < WGM ? (nM - fm) : WGM;
;         u.pm = fm + ((wgid % nig) % gsz); u.pn = (wgid % nig) / gsz; return true;
.LBB0_250:
	s_add_i32 s50, s50, 1
	s_mul_i32 s0, s50, s40
	s_mul_hi_u32 s1, s50, s88
	s_add_i32 s1, s1, s0
	s_mul_i32 s0, s50, s88
	s_add_u32 s4, s0, s2
	s_addc_u32 s5, s1, s3
	v_cmp_gt_i64_e32 vcc, s[4:5], v[142:143]
	v_cmp_lt_i64_e64 s[0:1], s[4:5], v[140:141]
	s_cbranch_vccnz .LBB0_252
	s_ashr_i32 s5, s4, 31
	s_lshr_b32 s5, s5, 29
	s_add_i32 s5, s4, s5
	s_ashr_i32 s7, s5, 3
	s_and_b32 s5, s5, -8
	s_sub_i32 s4, s4, s5
	s_cmp_lt_i32 s4, 0
	s_movk_i32 s5, 0x161
	s_cselect_b32 s5, s5, 0x160
	s_mul_i32 s4, s5, s4
	s_add_i32 s4, s4, s7
	s_mul_hi_i32 s5, s4, 0x2e8ba2e9
	s_lshr_b32 s7, s5, 31
	s_ashr_i32 s5, s5, 5
	s_add_i32 s5, s5, s7
	s_lshl_b32 s7, s5, 3
	s_mulk_i32 s5, 0xb0
	s_sub_i32 s4, s4, s5
	s_lshr_b32 s16, s4, 3
	s_and_b32 s4, s4, 7
	s_add_i32 s57, s4, s7

;     __device__ bool next(int i, Unit& u) const {
;         const long L = (long)i * G + c; if (L >= nwg) return false;
;         int wgid = (int)L; { const int q = nwg / NXCD, r = nwg % NXCD, xcd = wgid % NXCD, off = wgid / NXCD; wgid = (xcd < r ? xcd * (q + 1) : r * (q + 1) + (xcd - r) * q) + off; }
;         const int nig = WGM * nN, gid = wgid / nig, fm = gid * WGM, gsz = (nM - fm) < WGM ? (nM - fm) : WGM;
;         u.pm = fm + ((wgid % nig) % gsz); u.pn = (wgid % nig) / gsz; return true;
.LBB0_354:
	s_ashr_i32 s6, s22, 3
	s_add_i32 s6, s38, s6
	s_ashr_i32 s7, s6, 31
	s_lshr_b32 s7, s7, 27
	s_add_i32 s7, s6, s7
	s_ashr_i32 s22, s7, 5
	s_lshl_b32 s22, s22, 3
	s_andn2_b32 s7, s7, 31
	s_sub_i32 s6, s6, s7
	s_lshr_b32 s53, s6, 3
	s_and_b32 s6, s6, 7
	s_add_i32 s54, s6, s22

;     __device__ bool next(int i, Unit& u) const {
;         const long L = (long)i * G + c; if (L >= nwg) return false;
;         int wgid = (int)L; { const int q = nwg / NXCD, r = nwg % NXCD, xcd = wgid % NXCD, off = wgid / NXCD; wgid = (xcd < r ? xcd * (q + 1) : r * (q + 1) + (xcd - r) * q) + off; }
;         const int nig = WGM * nN, gid = wgid / nig, fm = gid * WGM, gsz = (nM - fm) < WGM ? (nM - fm) : WGM;
;         u.pm = fm + ((wgid % nig) % gsz); u.pn = (wgid % nig) / gsz; return true;
; __device__ __forceinline__ void build_rstab(RsTab& T, LAS unsigned char* lds, const float* ss, const StaticOrder& S) {
;     ...
;     for (int i = 0;; ++i) { Unit u; if (!S.next(i, u)) break; const int pm = u.pm;
;         if (pm == p0 || pm == p1 || pm == p2 || pm == p3) continue;
;         if (p0 < 0) p0 = pm; else if (p1 < 0) p1 = pm; else if (p2 < 0) p2 = pm; else if (p3 < 0) p3 = pm; }
.LBB0_425:
	v_cmp_gt_i64_e32 vcc, s[4:5], v[2:3]
	v_cmp_lt_i64_e64 s[0:1], s[4:5], v[0:1]
	s_cbranch_vccnz .LBB0_427
	s_ashr_i32 s6, s4, 31
	s_lshr_b32 s6, s6, 29
	s_add_i32 s6, s4, s6
	s_ashr_i32 s7, s6, 3
	s_and_b32 s6, s6, -8
	s_sub_i32 s6, s4, s6
	s_cmp_lt_i32 s6, 0
	s_cselect_b32 s9, s8, 0xc0
	s_mul_i32 s6, s9, s6
	s_add_i32 s6, s6, s7
	s_mul_hi_i32 s7, s6, 0x2aaaaaab
	s_lshr_b32 s9, s7, 31
	s_ashr_i32 s7, s7, 4
	s_add_i32 s7, s7, s9
	s_lshl_b32 s9, s7, 3
	s_mulk_i32 s7, 0x60
	s_sub_i32 s6, s6, s7
	s_and_b32 s6, s6, 7
	s_add_i32 s9, s6, s9

;     __device__ bool next(int i, Unit& u) const {
;         const long L = (long)i * G + c; if (L >= nwg) return false;
;         int wgid = (int)L; { const int q = nwg / NXCD, r = nwg % NXCD, xcd = wgid % NXCD, off = wgid / NXCD; wgid = (xcd < r ? xcd * (q + 1) : r * (q + 1) + (xcd - r) * q) + off; }
;         const int nig = WGM * nN, gid = wgid / nig, fm = gid * WGM, gsz = (nM - fm) < WGM ? (nM - fm) : WGM;
;         u.pm = fm + ((wgid % nig) % gsz); u.pn = (wgid % nig) / gsz; return true;
.LBB0_451:
	s_add_i32 s56, s56, 1
	s_mul_i32 s0, s56, s44
	s_mul_hi_u32 s1, s56, s88
	s_add_i32 s1, s1, s0
	s_mul_i32 s0, s56, s88
	s_add_u32 s4, s0, s2
	s_addc_u32 s5, s1, s3
	v_cmp_gt_i64_e32 vcc, s[4:5], v[148:149]
	v_cmp_lt_i64_e64 s[0:1], s[4:5], v[146:147]
	s_cbranch_vccnz .LBB0_453
	s_ashr_i32 s5, s4, 31
	s_lshr_b32 s5, s5, 29
	s_add_i32 s5, s4, s5
	s_ashr_i32 s7, s5, 3
	s_and_b32 s5, s5, -8
	s_sub_i32 s4, s4, s5
	s_cmp_lt_i32 s4, 0
	s_movk_i32 s5, 0xc1
	s_cselect_b32 s5, s5, 0xc0
	s_mul_i32 s4, s5, s4
	s_add_i32 s4, s4, s7
	s_mul_hi_i32 s5, s4, 0x2aaaaaab
	s_lshr_b32 s7, s5, 31
	s_ashr_i32 s5, s5, 4
	s_add_i32 s5, s5, s7
	s_lshl_b32 s7, s5, 3
	s_mulk_i32 s5, 0x60
	s_sub_i32 s4, s4, s5
	s_lshr_b32 s52, s4, 3
	s_and_b32 s4, s4, 7
	s_add_i32 s62, s4, s7

; __device__ __forceinline__ void att_qs(bf16x8 (&pn)[4], f32x16 (&o)[4], f32x16& osum, f32x16& negm, const bf16x8 (&qf)[4], float& m_hat, ...
;     ...
;     if (first_tile) {
; #pragma unroll
;         for (int r = 0; r < 16; ++r) { if (crow(r, hi) >= NMETA) c0[r] = -INFINITY; c1[r] = -INFINITY; }
;     }
;     asm volatile("s_nop 15\n\ts_nop 7" : "+v"(c0), "+v"(c1));
;     float rm;
;     { float a = max3a(c0[0], c0[1], c0[2]), b = max3a(c1[0], c1[1], c1[2]);
; #pragma unroll
;       for (int r = 3; r < 15; r += 2) { a = max3a(a, c0[r], c0[r + 1]); b = max3a(b, c1[r], c1[r + 1]); }
;       rm = max3a(a, b, c0[15]); rm = max3a(rm, c1[15], c1[15]); }
;     rm = xhalf_max(rm);
;     if (first_tile) {
;         m_hat += rm;
; #pragma unroll
;         for (int r = 0; r < 16; ++r) { c0[r] -= rm; c1[r] -= rm; negm[r] = -m_hat; }
;     } else if (__any(rm > 8.0f)) {
;         const float dl = fmaxf(rm, 0.f); m_hat += dl; const float f = __builtin_amdgcn_exp2f(-dl);
; #pragma unroll
;         for (int r = 0; r < 16; ++r) { c0[r] -= dl; c1[r] -= dl; negm[r] = -m_hat; }
;         if (hi == 0) scr[i32] = f;
;         asm volatile("s_waitcnt lgkmcnt(0)" ::: "memory");
; #pragma unroll
;         for (int r = 0; r < 16; ++r) { const float fr_ = scr[crow(r, hi)]; osum[r] *= fr_;
; #pragma unroll
;             for (int d = 0; d < 4; ++d) o[d][r] *= fr_; }
;     }
;     unsigned paw[16];
; #pragma unroll
;     for (int g = 0; g < 8; ++g) { const int b = (4 * g) & 15;
;         const float v0 = __builtin_amdgcn_exp2f(g < 4 ? c0[b] : c1[b]), v1 = __builtin_amdgcn_exp2f(g < 4 ? c0[b + 1] : c1[b + 1]);
;         const float v2 = __builtin_amdgcn_exp2f(g < 4 ? c0[b + 2] : c1[b + 2]), v3 = __builtin_amdgcn_exp2f(g < 4 ? c0[b + 3] : c1[b + 3]);
;         paw[2 * g] = pk2(v0, v1); paw[2 * g + 1] = pk2(v2, v3); }
; #pragma unroll
;     for (int k = 0; k < 4; ++k) { u32x4 w; w.x = paw[4 * k]; w.y = paw[4 * k + 1]; w.z = paw[4 * k + 2]; w.w = paw[4 * k + 3]; pn[k] = __builtin_bit_cast(bf16x8, w); }
;     __builtin_amdgcn_s_setprio(0);
; __device__ __forceinline__ void attn_unit(LAS unsigned char* lds, const bf16_t* Qb, const unsigned char* Kimg, const unsigned char* Vimg, bf16_t* AO, int b, int h, int qpos0, int ntiles, int store_limit, ...
;     ...
;         for (int tt = 0; tt < ntiles; ++tt) {
;             ATT_COMMON(tt)
.LBB0_679:
	v_mov_b32_e32 v30, v16
	v_mov_b32_e32 v31, v16
	v_mov_b32_e32 v17, v16
	v_mov_b32_e32 v18, v16
	v_mov_b32_e32 v19, v16
	v_mov_b32_e32 v20, v16
	v_mov_b32_e32 v21, v16
	v_mov_b32_e32 v22, v16
	v_mov_b32_e32 v23, v16
	v_mov_b32_e32 v24, v16
	v_mov_b32_e32 v25, v16
	v_mov_b32_e32 v26, v16
	v_mov_b32_e32 v27, v16
	v_mov_b32_e32 v28, v16
	v_mov_b32_e32 v29, v16
	v_mov_b64_e32 v[62:63], v[30:31]
	v_mov_b32_e32 v40, v16
	v_mov_b32_e32 v41, v16
	v_mov_b32_e32 v42, v16
	v_mov_b32_e32 v43, v16
	v_mov_b32_e32 v44, v16
	v_mov_b32_e32 v45, v16
	v_mov_b32_e32 v46, v16
	v_mov_b32_e32 v47, v16
	v_mov_b64_e32 v[60:61], v[28:29]
	v_mov_b64_e32 v[58:59], v[26:27]
	v_mov_b64_e32 v[56:57], v[24:25]
	v_mov_b64_e32 v[54:55], v[22:23]
	v_mov_b64_e32 v[52:53], v[20:21]
	v_mov_b64_e32 v[50:51], v[18:19]
	v_mov_b64_e32 v[48:49], v[16:17]
	s_nop 15
	s_nop 7
	s_nop 0
	v_max3_f32 v0, v32, v33, v34
	v_max3_f32 v2, v48, v49, v50
	s_nop 0
	v_max3_f32 v0, v0, v35, v36
	v_max3_f32 v2, v2, v51, v52
	s_nop 0
	v_max3_f32 v0, v0, v37, v38
	v_max3_f32 v2, v2, v53, v54
	s_nop 0
	v_max3_f32 v0, v0, v39, v40
	v_max3_f32 v2, v2, v55, v56
	s_nop 0
	v_max3_f32 v0, v0, v41, v42
	v_max3_f32 v2, v2, v57, v58
	s_nop 0
	v_max3_f32 v0, v0, v43, v44
	v_max3_f32 v2, v2, v59, v60
	s_nop 0
	v_max3_f32 v0, v0, v45, v46
	v_max3_f32 v2, v2, v61, v62
	s_nop 0
	v_max3_f32 v0, v0, v2, v47
	s_nop 0
	v_max3_f32 v0, v0, v63, v63
	s_nop 0
	v_mov_b32_e32 v2, v0
	s_nop 1
	v_permlane32_swap_b32_e32 v0, v2
	v_max_f32_e32 v2, v2, v2
	v_max_f32_e32 v0, v0, v0
	v_max_f32_e32 v0, v0, v2
	v_sub_f32_e32 v2, v48, v0
	v_sub_f32_e32 v3, v49, v0
	v_exp_f32_e32 v2, v2
	v_exp_f32_e32 v3, v3
	v_sub_f32_e32 v4, v50, v0
	v_sub_f32_e32 v5, v51, v0
	v_sub_f32_e32 v6, v52, v0
	v_sub_f32_e32 v7, v53, v0
	v_sub_f32_e32 v8, v54, v0
	v_sub_f32_e32 v9, v55, v0
	v_sub_f32_e32 v19, v32, v0
	v_sub_f32_e32 v31, v44, v0
	v_sub_f32_e32 v32, v45, v0
	v_exp_f32_e32 v8, v8
	v_exp_f32_e32 v9, v9
	v_exp_f32_e32 v6, v6
	v_exp_f32_e32 v7, v7
	v_exp_f32_e32 v4, v4
	v_exp_f32_e32 v5, v5
	v_cvt_pk_bf16_f32 v124, v2, v3
	v_exp_f32_e32 v2, v31
	v_exp_f32_e32 v3, v32
	v_sub_f32_e32 v20, v33, v0
	v_sub_f32_e32 v21, v34, v0
	v_sub_f32_e32 v23, v36, v0
	v_sub_f32_e32 v24, v37, v0
	v_sub_f32_e32 v27, v40, v0
	v_sub_f32_e32 v28, v41, v0
	v_sub_f32_e32 v29, v42, v0
	v_sub_f32_e32 v30, v43, v0
	v_sub_f32_e32 v33, v46, v0
	v_sub_f32_e32 v34, v47, v0
	v_cvt_pk_bf16_f32 v127, v8, v9
	v_exp_f32_e32 v8, v33
	v_exp_f32_e32 v9, v34
	v_cvt_pk_bf16_f32 v126, v6, v7
	v_cvt_pk_bf16_f32 v125, v4, v5
	v_exp_f32_e32 v4, v29
	v_exp_f32_e32 v5, v30
	v_exp_f32_e32 v6, v27
	v_exp_f32_e32 v7, v28
	v_cvt_pk_bf16_f32 v116, v2, v3
	v_exp_f32_e32 v2, v23
	v_exp_f32_e32 v3, v24
	v_sub_f32_e32 v10, v56, v0
	v_sub_f32_e32 v11, v57, v0
	v_sub_f32_e32 v12, v58, v0
	v_sub_f32_e32 v13, v59, v0
	v_sub_f32_e32 v14, v60, v0
	v_sub_f32_e32 v15, v61, v0
	v_sub_f32_e32 v17, v62, v0
	v_sub_f32_e32 v18, v63, v0
	v_sub_f32_e32 v22, v35, v0
	v_sub_f32_e32 v25, v38, v0
	v_sub_f32_e32 v26, v39, v0
	v_exp_f32_e32 v17, v17
	v_exp_f32_e32 v15, v15
	v_exp_f32_e32 v12, v12
	v_exp_f32_e32 v13, v13
	v_exp_f32_e32 v10, v10
	v_exp_f32_e32 v11, v11
	v_exp_f32_e32 v14, v14
	v_cvt_pk_bf16_f32 v117, v8, v9
	v_exp_f32_e32 v8, v25
	v_exp_f32_e32 v9, v26
	v_cvt_pk_bf16_f32 v115, v4, v5
	v_cvt_pk_bf16_f32 v114, v6, v7
	v_exp_f32_e32 v4, v21
	v_exp_f32_e32 v5, v22
	v_exp_f32_e32 v6, v19
	v_exp_f32_e32 v7, v20
	v_cvt_pk_bf16_f32 v136, v2, v3
	v_exp_f32_e32 v2, v18
	v_cvt_pk_bf16_f32 v121, v12, v13
	v_cvt_pk_bf16_f32 v120, v10, v11
	v_cvt_pk_bf16_f32 v137, v8, v9
	v_cvt_pk_bf16_f32 v135, v4, v5
	v_cvt_pk_bf16_f32 v134, v6, v7
	v_cvt_pk_bf16_f32 v122, v14, v15
	v_cvt_pk_bf16_f32 v123, v17, v2
	s_setprio 0
	s_min_u32 s9, s52, 2
	s_lshl_b32 s16, s9, 14
	s_add_i32 s9, s28, 0x8000
	v_lshl_add_u64 v[2:3], v[178:179], 0, s[16:17]
	s_mov_b32 s11, m0
	s_mov_b32 m0, s9
	s_nop 0
	global_load_lds_dwordx4 v[2:3], off
	s_mov_b32 m0, s11
	v_lshl_add_u64 v[2:3], v[2:3], 0, s[22:23]
	s_add_i32 s9, s28, 0xa000
	s_mov_b32 s11, m0
	s_mov_b32 m0, s9
	s_nop 0
	global_load_lds_dwordx4 v[2:3], off
	s_mov_b32 m0, s11
	s_add_i32 s10, s28, 0x18000
	v_lshl_add_u64 v[2:3], v[180:181], 0, s[16:17]
	s_mov_b32 s9, m0
	s_mov_b32 m0, s10
	s_nop 0
	global_load_lds_dwordx4 v[2:3], off
	s_mov_b32 m0, s9
	v_lshl_add_u64 v[2:3], v[2:3], 0, s[22:23]
	s_add_i32 s9, s28, 0x1a000
	s_mov_b32 s10, m0
	s_mov_b32 m0, s9
	s_nop 0
	global_load_lds_dwordx4 v[2:3], off
	s_mov_b32 m0, s10
	s_waitcnt vmcnt(4) lgkmcnt(0)
	s_barrier
	s_cmp_eq_u32 s50, 1
	s_cbranch_scc1 .LBB0_692
	v_add_f32_e32 v17, 0, v0
	v_mov_b32_e32 v14, v1
	v_mov_b32_e32 v15, v1
	v_xor_b32_e32 v98, 0x80000000, v17
	v_mov_b32_e32 v0, v1
	v_mov_b32_e32 v2, v1
	v_mov_b32_e32 v3, v1
	v_mov_b32_e32 v4, v1
	v_mov_b32_e32 v5, v1
	v_mov_b32_e32 v6, v1
	v_mov_b32_e32 v7, v1
	v_mov_b32_e32 v8, v1
	v_mov_b32_e32 v9, v1
	v_mov_b32_e32 v10, v1
	v_mov_b32_e32 v11, v1
	v_mov_b32_e32 v12, v1
	v_mov_b32_e32 v13, v1
	v_mov_b64_e32 v[48:49], v[14:15]
	v_mov_b64_e32 v[64:65], v[14:15]
	v_mov_b64_e32 v[80:81], v[14:15]
	v_mov_b64_e32 v[96:97], v[14:15]
	v_mov_b64_e32 v[32:33], v[14:15]
	s_sub_i32 s55, 0x4f, s46
	s_mov_b32 s56, 1
	s_mov_b32 s57, 0xc000
	v_mov_b64_e32 v[46:47], v[12:13]
	v_mov_b64_e32 v[44:45], v[10:11]
	v_mov_b64_e32 v[42:43], v[8:9]
	v_mov_b64_e32 v[40:41], v[6:7]
	v_mov_b64_e32 v[38:39], v[4:5]
	v_mov_b64_e32 v[36:37], v[2:3]
	v_mov_b64_e32 v[34:35], v[0:1]
	v_mov_b64_e32 v[62:63], v[12:13]
	v_mov_b64_e32 v[60:61], v[10:11]
	v_mov_b64_e32 v[58:59], v[8:9]
	v_mov_b64_e32 v[56:57], v[6:7]
	v_mov_b64_e32 v[54:55], v[4:5]
	v_mov_b64_e32 v[52:53], v[2:3]
	v_mov_b64_e32 v[50:51], v[0:1]
	v_mov_b64_e32 v[78:79], v[12:13]
	v_mov_b64_e32 v[76:77], v[10:11]
	v_mov_b64_e32 v[74:75], v[8:9]
	v_mov_b64_e32 v[72:73], v[6:7]
	v_mov_b64_e32 v[70:71], v[4:5]
	v_mov_b64_e32 v[68:69], v[2:3]
	v_mov_b64_e32 v[66:67], v[0:1]
	v_mov_b64_e32 v[94:95], v[12:13]
	v_mov_b64_e32 v[92:93], v[10:11]
	v_mov_b64_e32 v[90:91], v[8:9]
	v_mov_b64_e32 v[88:89], v[6:7]
	v_mov_b64_e32 v[86:87], v[4:5]
	v_mov_b64_e32 v[84:85], v[2:3]
	v_mov_b64_e32 v[82:83], v[0:1]
	v_mov_b64_e32 v[30:31], v[12:13]
	v_mov_b64_e32 v[28:29], v[10:11]
	v_mov_b64_e32 v[26:27], v[8:9]
	v_mov_b64_e32 v[24:25], v[6:7]
	v_mov_b64_e32 v[22:23], v[4:5]
	v_mov_b64_e32 v[20:21], v[2:3]
	v_mov_b64_e32 v[18:19], v[0:1]
	v_mov_b32_e32 v99, v98
	v_mov_b32_e32 v100, v98
	v_mov_b32_e32 v101, v98
	v_mov_b32_e32 v102, v98
	v_mov_b32_e32 v103, v98
	v_mov_b32_e32 v104, v98
	v_mov_b32_e32 v105, v98
	v_mov_b32_e32 v106, v98
	v_mov_b32_e32 v107, v98
	v_mov_b32_e32 v108, v98
	v_mov_b32_e32 v109, v98
	v_mov_b32_e32 v110, v98
	v_mov_b32_e32 v111, v98
	v_mov_b32_e32 v112, v98
	v_mov_b32_e32 v113, v98
	s_branch .LBB0_684
	s_nop 0
	s_nop 0

;     __device__ bool next(int i, Unit& u) const {
;         const long L = (long)i * G + c; if (L >= nwg) return false;
;         int wgid = (int)L; { const int q = nwg / NXCD, r = nwg % NXCD, xcd = wgid % NXCD, off = wgid / NXCD; wgid = (xcd < r ? xcd * (q + 1) : r * (q + 1) + (xcd - r) * q) + off; }
;         const int nig = WGM * nN, gid = wgid / nig, fm = gid * WGM, gsz = (nM - fm) < WGM ? (nM - fm) : WGM;
;         u.pm = fm + ((wgid % nig) % gsz); u.pn = (wgid % nig) / gsz; return true;
.LBB0_798:
	s_ashr_i32 s6, s22, 3
	s_add_i32 s6, s26, s6
	s_ashr_i32 s7, s6, 31
	s_lshr_b32 s7, s7, 27
	s_add_i32 s7, s6, s7
	s_ashr_i32 s22, s7, 5
	s_lshl_b32 s23, s22, 3
	s_andn2_b32 s7, s7, 31
	s_sub_i32 s6, s6, s7
	s_lshr_b32 s22, s6, 3
	s_and_b32 s6, s6, 7
	s_add_i32 s53, s6, s23

;     __device__ bool next(int i, Unit& u) const {
;         const long L = (long)i * G + c; if (L >= nwg) return false;
;         int wgid = (int)L; { const int q = nwg / NXCD, r = nwg % NXCD, xcd = wgid % NXCD, off = wgid / NXCD; wgid = (xcd < r ? xcd * (q + 1) : r * (q + 1) + (xcd - r) * q) + off; }
;         const int nig = WGM * nN, gid = wgid / nig, fm = gid * WGM, gsz = (nM - fm) < WGM ? (nM - fm) : WGM;
;         u.pm = fm + ((wgid % nig) % gsz); u.pn = (wgid % nig) / gsz; return true;
.LBB0_878:
	s_add_i32 s50, s50, 1
	s_mul_i32 s0, s50, s40
	s_mul_hi_u32 s1, s50, s88
	s_add_i32 s1, s1, s0
	s_mul_i32 s0, s50, s88
	s_add_u32 s4, s0, s2
	s_addc_u32 s5, s1, s3
	v_cmp_gt_i64_e32 vcc, s[4:5], v[142:143]
	v_cmp_lt_i64_e64 s[0:1], s[4:5], v[140:141]
	s_cbranch_vccnz .LBB0_880
	s_ashr_i32 s5, s4, 31
	s_lshr_b32 s5, s5, 29
	s_add_i32 s5, s4, s5
	s_ashr_i32 s7, s5, 3
	s_and_b32 s5, s5, -8
	s_sub_i32 s4, s4, s5
	s_cmp_lt_i32 s4, 0
	s_cselect_b32 s5, s53, 0x160
	s_mul_i32 s4, s5, s4
	s_add_i32 s4, s4, s7
	s_mul_hi_i32 s5, s4, 0x2e8ba2e9
	s_lshr_b32 s7, s5, 31
	s_ashr_i32 s5, s5, 5
	s_add_i32 s5, s5, s7
	s_lshl_b32 s7, s5, 3
	s_mulk_i32 s5, 0xb0
	s_sub_i32 s4, s4, s5
	s_lshr_b32 s16, s4, 3
	s_and_b32 s4, s4, 7
	s_add_i32 s59, s4, s7

;     __device__ bool next(int i, Unit& u) const {
;         const long L = (long)i * G + c; if (L >= nwg) return false;
;         int wgid = (int)L; { const int q = nwg / NXCD, r = nwg % NXCD, xcd = wgid % NXCD, off = wgid / NXCD; wgid = (xcd < r ? xcd * (q + 1) : r * (q + 1) + (xcd - r) * q) + off; }
;         const int nig = WGM * nN, gid = wgid / nig, fm = gid * WGM, gsz = (nM - fm) < WGM ? (nM - fm) : WGM;
;         u.pm = fm + ((wgid % nig) % gsz); u.pn = (wgid % nig) / gsz; return true;
.LBB0_982:
	s_ashr_i32 s6, s22, 3
	s_add_i32 s6, s36, s6
	s_ashr_i32 s7, s6, 31
	s_lshr_b32 s7, s7, 27
	s_add_i32 s7, s6, s7
	s_ashr_i32 s22, s7, 5
	s_lshl_b32 s22, s22, 3
	s_andn2_b32 s7, s7, 31
	s_sub_i32 s6, s6, s7
	s_lshr_b32 s53, s6, 3
	s_and_b32 s6, s6, 7
	s_add_i32 s54, s6, s22

;     __device__ bool next(int i, Unit& u) const {
;         const long L = (long)i * G + c; if (L >= nwg) return false;
;         int wgid = (int)L; { const int q = nwg / NXCD, r = nwg % NXCD, xcd = wgid % NXCD, off = wgid / NXCD; wgid = (xcd < r ? xcd * (q + 1) : r * (q + 1) + (xcd - r) * q) + off; }
;         const int nig = WGM * nN, gid = wgid / nig, fm = gid * WGM, gsz = (nM - fm) < WGM ? (nM - fm) : WGM;
;         u.pm = fm + ((wgid % nig) % gsz); u.pn = (wgid % nig) / gsz; return true;
; __device__ __forceinline__ void build_rstab(RsTab& T, LAS unsigned char* lds, const float* ss, const StaticOrder& S) {
;     ...
;     for (int i = 0;; ++i) { Unit u; if (!S.next(i, u)) break; const int pm = u.pm;
;         if (pm == p0 || pm == p1 || pm == p2 || pm == p3) continue;
;         if (p0 < 0) p0 = pm; else if (p1 < 0) p1 = pm; else if (p2 < 0) p2 = pm; else if (p3 < 0) p3 = pm; }
.LBB0_1043:
	s_ashr_i32 s6, s10, 3
	s_add_i32 s6, s12, s6
	s_ashr_i32 s7, s6, 31
	s_lshr_b32 s7, s7, 26
	s_add_i32 s7, s6, s7
	s_ashr_i32 s10, s7, 6
	s_lshl_b32 s10, s10, 3
	s_andn2_b32 s7, s7, 63
	s_sub_i32 s6, s6, s7
	s_and_b32 s6, s6, 7
	s_add_i32 s10, s6, s10

;     __device__ bool next(int i, Unit& u) const {
;         const long L = (long)i * G + c; if (L >= nwg) return false;
;         int wgid = (int)L; { const int q = nwg / NXCD, r = nwg % NXCD, xcd = wgid % NXCD, off = wgid / NXCD; wgid = (xcd < r ? xcd * (q + 1) : r * (q + 1) + (xcd - r) * q) + off; }
;         const int nig = WGM * nN, gid = wgid / nig, fm = gid * WGM, gsz = (nM - fm) < WGM ? (nM - fm) : WGM;
;         u.pm = fm + ((wgid % nig) % gsz); u.pn = (wgid % nig) / gsz; return true;
.LBB0_1077:
	s_ashr_i32 s4, s7, 3
	s_add_i32 s4, s23, s4
	s_ashr_i32 s5, s4, 31
	s_lshr_b32 s5, s5, 26
	s_add_i32 s5, s4, s5
	s_ashr_i32 s7, s5, 6
	s_lshl_b32 s7, s7, 3
	s_andn2_b32 s5, s5, 63
	s_sub_i32 s4, s4, s5
	s_lshr_b32 s22, s4, 3
	s_and_b32 s4, s4, 7
	s_add_i32 s57, s4, s7

;     __device__ bool next(int i, Unit& u) const {
;         const long L = (long)i * G + c; if (L >= nwg) return false;
;         int wgid = (int)L; { const int q = nwg / NXCD, r = nwg % NXCD, xcd = wgid % NXCD, off = wgid / NXCD; wgid = (xcd < r ? xcd * (q + 1) : r * (q + 1) + (xcd - r) * q) + off; }
;         const int nig = WGM * nN, gid = wgid / nig, fm = gid * WGM, gsz = (nM - fm) < WGM ? (nM - fm) : WGM;
;         u.pm = fm + ((wgid % nig) % gsz); u.pn = (wgid % nig) / gsz; return true;
.LBB0_1244:
	s_ashr_i32 s6, s26, 3
	s_add_i32 s6, s28, s6
	s_ashr_i32 s7, s6, 31
	s_lshr_b32 s7, s7, 27
	s_add_i32 s7, s6, s7
	s_ashr_i32 s26, s7, 5
	s_lshl_b32 s27, s26, 3
	s_andn2_b32 s7, s7, 31
	s_sub_i32 s6, s6, s7
	s_lshr_b32 s26, s6, 3
	s_and_b32 s6, s6, 7
	s_add_i32 s56, s6, s27

;     __device__ bool next(int i, Unit& u) const {
;         const long L = (long)i * G + c; if (L >= nwg) return false;
;         int wgid = (int)L; { const int q = nwg / NXCD, r = nwg % NXCD, xcd = wgid % NXCD, off = wgid / NXCD; wgid = (xcd < r ? xcd * (q + 1) : r * (q + 1) + (xcd - r) * q) + off; }
;         const int nig = WGM * nN, gid = wgid / nig, fm = gid * WGM, gsz = (nM - fm) < WGM ? (nM - fm) : WGM;
;         u.pm = fm + ((wgid % nig) % gsz); u.pn = (wgid % nig) / gsz; return true;
.LBB0_1581:
	s_ashr_i32 s26, s29, 3
	s_add_i32 s26, s38, s26
	s_ashr_i32 s27, s26, 31
	s_lshr_b32 s27, s27, 27
	s_add_i32 s27, s26, s27
	s_ashr_i32 s28, s27, 5
	s_lshl_b32 s28, s28, 3
	s_andn2_b32 s27, s27, 31
	s_sub_i32 s27, s26, s27
	s_lshr_b32 s26, s27, 3
	s_and_b32 s27, s27, 7
	s_add_i32 s67, s27, s28
	s_andn2_b64 vcc, exec, s[0:1]
	s_mov_b64 s[0:1], -1
	s_cbranch_vccnz .LBB0_1552

;     __device__ bool next(int i, Unit& u) const {
;         const long L = (long)i * G + c; if (L >= nwg) return false;
;         int wgid = (int)L; { const int q = nwg / NXCD, r = nwg % NXCD, xcd = wgid % NXCD, off = wgid / NXCD; wgid = (xcd < r ? xcd * (q + 1) : r * (q + 1) + (xcd - r) * q) + off; }
;         const int nig = WGM * nN, gid = wgid / nig, fm = gid * WGM, gsz = (nM - fm) < WGM ? (nM - fm) : WGM;
;         u.pm = fm + ((wgid % nig) % gsz); u.pn = (wgid % nig) / gsz; return true;
.LBB0_1637:
	s_add_i32 s46, s46, 1
	s_mul_i32 s0, s46, s36
	s_mul_hi_u32 s1, s46, s88
	s_add_i32 s1, s1, s0
	s_mul_i32 s0, s46, s88
	s_add_u32 s4, s0, s2
	s_addc_u32 s5, s1, s3
	v_cmp_gt_i64_e32 vcc, s[4:5], v[142:143]
	v_cmp_lt_i64_e64 s[0:1], s[4:5], v[140:141]
	s_cbranch_vccnz .LBB0_1639
	s_ashr_i32 s5, s4, 31
	s_lshr_b32 s5, s5, 29
	s_add_i32 s5, s4, s5
	s_ashr_i32 s7, s5, 3
	s_and_b32 s5, s5, -8
	s_sub_i32 s4, s4, s5
	s_cmp_lt_i32 s4, 0
	s_cselect_b32 s5, s49, 0x160
	s_mul_i32 s4, s5, s4
	s_add_i32 s4, s4, s7
	s_mul_hi_i32 s5, s4, 0x2e8ba2e9
	s_lshr_b32 s7, s5, 31
	s_ashr_i32 s5, s5, 5
	s_add_i32 s5, s5, s7
	s_lshl_b32 s7, s5, 3
	s_mulk_i32 s5, 0xb0
	s_sub_i32 s4, s4, s5
	s_lshr_b32 s16, s4, 3
	s_and_b32 s4, s4, 7
	s_add_i32 s55, s4, s7

;     __device__ bool next(int i, Unit& u) const {
;         const long L = (long)i * G + c; if (L >= nwg) return false;
;         int wgid = (int)L; { const int q = nwg / NXCD, r = nwg % NXCD, xcd = wgid % NXCD, off = wgid / NXCD; wgid = (xcd < r ? xcd * (q + 1) : r * (q + 1) + (xcd - r) * q) + off; }
;         const int nig = WGM * nN, gid = wgid / nig, fm = gid * WGM, gsz = (nM - fm) < WGM ? (nM - fm) : WGM;
;         u.pm = fm + ((wgid % nig) % gsz); u.pn = (wgid % nig) / gsz; return true;
.LBB0_1742:
	s_ashr_i32 s6, s20, 3
	s_add_i32 s6, s28, s6
	s_ashr_i32 s7, s6, 31
	s_lshr_b32 s7, s7, 27
	s_add_i32 s7, s6, s7
	s_ashr_i32 s20, s7, 5
	s_lshl_b32 s20, s20, 3
	s_andn2_b32 s7, s7, 31
	s_sub_i32 s6, s6, s7
	s_lshr_b32 s49, s6, 3
	s_and_b32 s6, s6, 7
	s_add_i32 s50, s6, s20
